# attention queues: items ordered in groups of (heavy diff, light diff, FoX, FoX), q-blocks descending
# baseline (speedup 1.0000x reference)
.LBB0_835:
	s_or_b64 exec, exec, s[0:1]
	s_waitcnt lgkmcnt(0)
	s_barrier
	ds_read_b32 v0, v202
	s_movk_i32 s0, 0x20b
	s_waitcnt lgkmcnt(0)
	s_barrier
	v_cmp_lt_i32_e32 vcc, s0, v0
	v_readfirstlane_b32 s54, v0
	s_mov_b64 s[0:1], -1
	s_cbranch_vccnz .LBB0_830
	s_cmp_lt_i32 s54, 8
	s_cbranch_scc1 .LBB0_846
	s_mov_b64 s[36:37], -1
	s_cmp_gt_u32 s54, 11
	s_mov_b64 s[38:39], -1
	s_cbranch_scc0 .LBB0_843
	s_add_i32 s4, s54, -12
	s_lshr_b32 s30, s4, 2
	s_and_b32 s31, s4, 3
	s_lshl_b32 s30, s30, 1
	s_add_i32 s30, s30, s31
	s_cmp_lt_u32 s31, 2
	s_cselect_b32 s31, 12, 0x10a
	s_add_i32 s54, s30, s31
	s_mov_b64 s[4:5], -1
	s_cmpk_gt_u32 s54, 0x10b
	s_cbranch_scc0 .LBB0_840
	s_add_i32 s6, s54, 0xfffffef4
	s_lshr_b32 s30, s6, 6
	s_and_b32 s30, s30, 0x3fffffe
	s_add_i32 s30, s30, s70
	s_not_b32 s6, s6
	s_and_b32 s31, s54, 1
	s_bfe_u32 s50, s6, 0x60001
	s_and_b32 s6, s30, 6
	s_lshr_b32 s55, s30, 3
	s_or_b32 s6, s6, s31
	s_mov_b64 s[38:39], 0
